# prologue rope-table loop: next iteration's position load issued at the top of the current iteration (latency hidden behind the f64/sincos math)
# baseline (speedup 1.0000x reference)
.LBB0_66:
	v_readlane_b32 s0, v249, 0
	v_readlane_b32 s1, v249, 1
	s_load_dwordx2 s[48:49], s[0:1], 0x70
	v_lshl_add_u32 v2, s2, 9, v24
	s_mov_b32 s4, 0x100000
	s_lshl_b32 s46, s86, 9
	v_cmp_gt_i32_e32 vcc, s4, v2
	v_ashrrev_i32_e32 v3, 31, v2
	s_and_saveexec_b64 s[50:51], vcc
	s_cbranch_execz .LBB0_77
	v_and_b32_e32 v4, 31, v24
	s_mov_b32 s4, 0x979a371
	v_cvt_f64_u32_e32 v[4:5], v4
	s_mov_b32 s5, 0xbfda934f
	v_mul_f64 v[4:5], v[4:5], s[4:5]
	v_rndne_f64_e32 v[6:7], v[4:5]
	s_mov_b32 s4, 0x3b39803f
	v_add_f64 v[8:9], v[4:5], -v[6:7]
	s_mov_b32 s5, 0x3c7abc9e
	v_mul_f64 v[10:11], v[8:9], s[4:5]
	s_mov_b32 s4, 0xfefa39ef
	s_mov_b32 s5, 0x3fe62e42
	v_fmac_f64_e32 v[10:11], s[4:5], v[8:9]
	s_mov_b32 s4, 0x6a5dcb37
	v_mov_b32_e32 v8, 0xfca7ab0c
	v_mov_b32_e32 v9, 0x3e928af3
	s_mov_b32 s5, 0x3e5ade15
	v_fmac_f64_e32 v[8:9], s[4:5], v[10:11]
	v_mov_b32_e32 v12, 0x623fde64
	v_mov_b32_e32 v13, 0x3ec71dee
	v_fmac_f64_e32 v[12:13], v[10:11], v[8:9]
	v_mov_b32_e32 v8, 0x7c89e6b0
	v_mov_b32_e32 v9, 0x3efa0199
	v_fmac_f64_e32 v[8:9], v[10:11], v[12:13]
	v_mov_b32_e32 v12, 0x14761f6e
	v_mov_b32_e32 v13, 0x3f2a01a0
	v_fmac_f64_e32 v[12:13], v[10:11], v[8:9]
	v_mov_b32_e32 v8, 0x1852b7b0
	v_mov_b32_e32 v9, 0x3f56c16c
	v_fmac_f64_e32 v[8:9], v[10:11], v[12:13]
	v_mov_b32_e32 v12, 0x11122322
	v_mov_b32_e32 v13, 0x3f811111
	v_fmac_f64_e32 v[12:13], v[10:11], v[8:9]
	v_mov_b32_e32 v8, 0x555502a1
	v_mov_b32_e32 v9, 0x3fa55555
	v_fmac_f64_e32 v[8:9], v[10:11], v[12:13]
	v_mov_b32_e32 v12, 0x55555511
	v_mov_b32_e32 v13, 0x3fc55555
	v_fmac_f64_e32 v[12:13], v[10:11], v[8:9]
	v_mov_b32_e32 v8, 11
	v_mov_b32_e32 v9, 0x3fe00000
	s_mov_b32 s4, 0
	v_fmac_f64_e32 v[8:9], v[10:11], v[12:13]
	s_mov_b32 s5, 0x40900000
	v_fma_f64 v[8:9], v[10:11], v[8:9], 1.0
	v_cmp_nlt_f64_e32 vcc, s[4:5], v[4:5]
	s_mov_b32 s4, 0
	v_fma_f64 v[8:9], v[10:11], v[8:9], 1.0
	v_cvt_i32_f64_e32 v6, v[6:7]
	s_mov_b32 s5, 0xc090cc00
	v_ldexp_f64 v[6:7], v[8:9], v6
	v_mov_b32_e32 v8, 0x7ff00000
	v_cmp_ngt_f64_e64 s[4:5], s[4:5], v[4:5]
	v_cndmask_b32_e32 v7, v8, v7, vcc
	s_and_b64 vcc, s[4:5], vcc
	v_cndmask_b32_e64 v5, 0, v7, s[4:5]
	v_cndmask_b32_e32 v4, 0, v6, vcc
	v_lshl_add_u64 v[6:7], v[2:3], 2, s[78:79]
	s_mov_b64 s[4:5], 0x5600000
	s_ashr_i32 s47, s46, 31
	s_mov_b32 s56, 0x6dc9c883
	s_mov_b32 s58, 0x54442d18
	s_mov_b32 s60, 0x33145c07
	v_lshl_add_u64 v[6:7], v[6:7], 0, s[4:5]
	s_lshl_b64 s[52:53], s[46:47], 2
	s_mov_b64 s[54:55], 0
	s_mov_b32 s57, 0x3fc45f30
	s_mov_b32 s59, 0xc01921fb
	s_mov_b32 s61, 0xbcb1a626
	s_brev_b32 s43, 18
	s_mov_b32 s45, 0xfe5163ab
	v_mov_b32_e32 v9, 0
	s_mov_b32 s47, 0x3c439041
	s_mov_b32 s64, 0xdb629599
	s_mov_b32 s65, 0xf534ddc0
	s_mov_b32 s66, 0xfc2757d1
	s_mov_b32 s67, 0x4e441529
	s_mov_b32 s68, 0xa2f9836e
	s_mov_b32 s69, 0x3fc90fda
	s_mov_b32 s71, 0x3f22f983
	s_mov_b32 s74, 0xbfc90fda
	v_mov_b32_e32 v10, 0x3c0881c4
	v_mov_b32_e32 v11, 0xbab64f3b
	s_brev_b32 s75, 1
	s_movk_i32 s76, 0x1f8
	s_mov_b32 s77, 0xfffff
	v_not_b32_e32 v12, 63
	v_not_b32_e32 v13, 31
	v_mov_b32_e32 v15, 0x7fc00000
	v_mov_b32_e32 v16, v2
	v_ashrrev_i32_e32 v102, 5, v16
	v_ashrrev_i32_e32 v103, 31, v102
	s_waitcnt lgkmcnt(0)
	v_lshl_add_u64 v[102:103], v[102:103], 2, s[16:17]
	global_load_dword v100, v[102:103], off
	s_waitcnt vmcnt(0)
	s_branch .LBB0_69

.LBB0_69:
	s_waitcnt vmcnt(2)
	v_mov_b32_e32 v8, v100
	v_add_u32_e32 v102, s46, v16
	v_ashrrev_i32_e32 v102, 5, v102
	v_min_i32_e32 v102, 0x7fff, v102
	v_ashrrev_i32_e32 v103, 31, v102
	v_lshl_add_u64 v[102:103], v[102:103], 2, s[16:17]
	global_load_dword v100, v[102:103], off
	v_cvt_f64_i32_e32 v[18:19], v8
	v_mul_f64 v[18:19], v[4:5], v[18:19]
	v_mul_f64 v[20:21], v[18:19], s[56:57]
	v_rndne_f64_e32 v[20:21], v[20:21]
	v_fmac_f64_e32 v[18:19], s[58:59], v[20:21]
	v_fmac_f64_e32 v[18:19], s[60:61], v[20:21]
	v_cvt_f32_f64_e32 v17, v[18:19]
	v_and_b32_e32 v18, 0x7fffffff, v17
	v_lshrrev_b32_e32 v8, 23, v18
	v_and_b32_e32 v19, 0x7fffff, v18
	v_cmp_nlt_f32_e64 s[10:11], |v17|, s43
	v_add_u32_e32 v20, 0xffffff88, v8
	v_or_b32_e32 v19, 0x800000, v19
	s_and_saveexec_b64 s[4:5], s[10:11]
	s_xor_b64 s[62:63], exec, s[4:5]
	s_cbranch_execz .LBB0_71
	v_cmp_lt_u32_e32 vcc, 63, v20
	v_mad_u64_u32 v[26:27], s[8:9], v19, s45, 0
	s_nop 0
	v_cndmask_b32_e32 v8, 0, v12, vcc
	v_add_u32_e32 v8, v8, v20
	v_cmp_lt_u32_e64 s[4:5], 31, v8
	s_nop 1
	v_cndmask_b32_e64 v21, 0, v13, s[4:5]
	v_add_u32_e32 v8, v21, v8
	v_cmp_lt_u32_e64 s[6:7], 31, v8
	s_nop 1
	v_cndmask_b32_e64 v21, 0, v13, s[6:7]
	v_add_u32_e32 v21, v21, v8
	v_mov_b32_e32 v8, v27
	v_mad_u64_u32 v[28:29], s[8:9], v19, s47, v[8:9]
	v_mov_b32_e32 v8, v29
	v_mad_u64_u32 v[30:31], s[8:9], v19, s64, v[8:9]
	v_mov_b32_e32 v8, v31
	v_mad_u64_u32 v[32:33], s[8:9], v19, s65, v[8:9]
	v_mov_b32_e32 v8, v33
	v_mad_u64_u32 v[34:35], s[8:9], v19, s66, v[8:9]
	v_mov_b32_e32 v8, v35
	v_mad_u64_u32 v[36:37], s[8:9], v19, s67, v[8:9]
	v_mov_b32_e32 v8, v37
	v_mad_u64_u32 v[38:39], s[8:9], v19, s68, v[8:9]
	v_cndmask_b32_e32 v22, v36, v32, vcc
	v_cndmask_b32_e32 v8, v38, v34, vcc
	v_cndmask_b32_e32 v29, v39, v36, vcc
	v_cndmask_b32_e64 v27, v8, v22, s[4:5]
	v_cndmask_b32_e64 v8, v29, v8, s[4:5]
	v_cndmask_b32_e32 v29, v34, v30, vcc
	v_cndmask_b32_e64 v22, v22, v29, s[4:5]
	v_sub_u32_e32 v31, 32, v21
	v_cmp_eq_u32_e64 s[8:9], 0, v21
	v_cndmask_b32_e32 v21, v32, v28, vcc
	v_cndmask_b32_e64 v8, v8, v27, s[6:7]
	v_cndmask_b32_e64 v27, v27, v22, s[6:7]
	v_cndmask_b32_e64 v28, v29, v21, s[4:5]
	v_alignbit_b32 v33, v8, v27, v31
	v_cndmask_b32_e64 v22, v22, v28, s[6:7]
	v_cndmask_b32_e32 v26, v30, v26, vcc
	v_cndmask_b32_e64 v8, v33, v8, s[8:9]
	v_alignbit_b32 v29, v27, v22, v31
	v_cndmask_b32_e64 v21, v21, v26, s[4:5]
	v_cndmask_b32_e64 v27, v29, v27, s[8:9]
	v_bfe_u32 v33, v8, 29, 1
	v_cndmask_b32_e64 v21, v28, v21, s[6:7]
	v_alignbit_b32 v29, v8, v27, 30
	v_sub_u32_e32 v34, 0, v33
	v_alignbit_b32 v26, v22, v21, v31
	v_xor_b32_e32 v29, v29, v34
	v_cndmask_b32_e64 v22, v26, v22, s[8:9]
	v_alignbit_b32 v26, v27, v22, 30
	v_ffbh_u32_e32 v27, v29
	v_min_u32_e32 v27, 32, v27
	v_alignbit_b32 v21, v22, v21, 30
	v_xor_b32_e32 v26, v26, v34
	v_sub_u32_e32 v28, 31, v27
	v_xor_b32_e32 v21, v21, v34
	v_alignbit_b32 v29, v29, v26, v28
	v_alignbit_b32 v21, v26, v21, v28
	v_alignbit_b32 v22, v29, v21, 9
	v_ffbh_u32_e32 v26, v22
	v_min_u32_e32 v26, 32, v26
	v_lshrrev_b32_e32 v32, 29, v8
	v_not_b32_e32 v28, v26
	v_alignbit_b32 v21, v22, v21, v28
	v_lshlrev_b32_e32 v22, 31, v32
	v_or_b32_e32 v28, 0x33000000, v22
	v_add_lshl_u32 v26, v26, v27, 23
	v_lshrrev_b32_e32 v21, 9, v21
	v_sub_u32_e32 v26, v28, v26
	v_or_b32_e32 v22, 0.5, v22
	v_lshlrev_b32_e32 v27, 23, v27
	v_or_b32_e32 v21, v26, v21
	v_lshrrev_b32_e32 v26, 9, v29
	v_sub_u32_e32 v22, v22, v27
	v_or_b32_e32 v22, v26, v22
	v_mul_f32_e32 v26, 0x3fc90fda, v22
	v_fma_f32 v27, v22, s69, -v26
	v_fmac_f32_e32 v27, 0x33a22168, v22
	v_fmac_f32_e32 v27, 0x3fc90fda, v21
	v_lshrrev_b32_e32 v8, 30, v8
	v_add_f32_e32 v22, v26, v27
	v_add_u32_e32 v21, v33, v8
